# G2 merge epilogues: redundant v_max(x,x) canonicalisations removed (on top of the paced version)
# speedup vs baseline: 1.0057x; 1.0057x over previous
.LBB0_1236:
	v_mov_b32_e32 v0, v234
	s_lshl_b32 s0, s10, 8
	s_add_i32 s0, s0, s46
	v_and_or_b32 v136, v0, 15, s0
	s_lshl_b32 s0, s11, 8
	v_lshrrev_b32_e32 v0, 1, v0
	v_mov_b64_e32 v[2:3], s[66:67]
	v_and_or_b32 v0, v0, 24, s0
	v_mad_i64_i32 v[2:3], s[0:1], v136, s29, v[2:3]
	s_lshl_b32 s0, s54, 11
	v_or_b32_e32 v132, s47, v0
	s_ashr_i32 s1, s0, 31
	v_lshl_add_u64 v[2:3], s[0:1], 1, v[2:3]
	v_ashrrev_i32_e32 v133, 31, v132
	v_lshl_add_u64 v[2:3], v[132:133], 1, v[2:3]
	s_mov_b64 s[0:1], 0x4800
	v_lshl_add_u64 v[2:3], v[2:3], 0, s[0:1]
	s_cmp_gt_i32 s54, 1
	s_mov_b64 s[0:1], -1
	s_mov_b32 s6, 0x90000
	s_mov_b32 s7, 0xa0000
	s_mov_b32 s8, 0xb0000
	s_cbranch_scc0 .LBB0_1239
	global_load_dwordx4 v[156:159], v[2:3], off
	global_load_dwordx4 v[160:163], v[2:3], off offset:256
	s_mov_b64 s[98:99], 0x7c000
	v_lshl_add_u64 v[250:251], v[2:3], 0, s[98:99]
	global_load_dwordx4 v[164:167], v[250:251], off
	global_load_dwordx4 v[168:171], v[250:251], off offset:256
	s_mov_b64 s[98:99], 0xf8000
	v_lshl_add_u64 v[250:251], v[2:3], 0, s[98:99]
	global_load_dwordx4 v[172:175], v[250:251], off
	global_load_dwordx4 v[176:179], v[250:251], off offset:256
	s_mov_b64 s[98:99], 0x174000
	v_lshl_add_u64 v[250:251], v[2:3], 0, s[98:99]
	global_load_dwordx4 v[180:183], v[250:251], off
	global_load_dwordx4 v[184:187], v[250:251], off offset:256
	s_mov_b64 s[98:99], 0x3e0000
	v_lshl_add_u64 v[250:251], v[2:3], 0, s[98:99]
	global_load_dwordx4 v[188:191], v[250:251], off
	global_load_dwordx4 v[192:195], v[250:251], off offset:256
	s_mov_b64 s[98:99], 0x45c000
	v_lshl_add_u64 v[250:251], v[2:3], 0, s[98:99]
	global_load_dwordx4 v[210:213], v[250:251], off
	global_load_dwordx4 v[214:217], v[250:251], off offset:256
	s_mov_b64 s[98:99], 0x4d8000
	v_lshl_add_u64 v[250:251], v[2:3], 0, s[98:99]
	global_load_dwordx4 v[228:231], v[250:251], off
	global_load_dwordx4 v[242:245], v[250:251], off offset:256
	s_mov_b64 s[98:99], 0x554000
	v_lshl_add_u64 v[250:251], v[2:3], 0, s[98:99]
	global_load_dwordx4 v[246:249], v[250:251], off
	v_ashrrev_i32_e32 v137, 31, v136
	v_lshlrev_b64 v[134:135], 12, v[136:137]
	s_mov_b32 s0, 0x7c000
	s_waitcnt vmcnt(0)
	v_lshlrev_b32_e32 v0, 16, v156
	v_max_f32_e32 v142, 0x1e3ce508, v0
	v_and_b32_e32 v0, 0xffff0000, v156
	v_max_f32_e32 v143, 0x1e3ce508, v0
	v_lshlrev_b32_e32 v0, 16, v157
	v_max_f32_e32 v138, 0x1e3ce508, v0
	v_and_b32_e32 v0, 0xffff0000, v157
	v_max_f32_e32 v139, 0x1e3ce508, v0
	v_lshlrev_b32_e32 v0, 16, v158
	v_pk_mul_f32 v[144:145], v[130:131], v[138:139]
	v_max_f32_e32 v138, 0x1e3ce508, v0
	v_and_b32_e32 v0, 0xffff0000, v158
	v_max_f32_e32 v139, 0x1e3ce508, v0
	v_lshlrev_b32_e32 v0, 16, v159
	v_pk_mul_f32 v[146:147], v[124:125], v[138:139]
	v_max_f32_e32 v138, 0x1e3ce508, v0
	v_and_b32_e32 v0, 0xffff0000, v159
	v_pk_mul_f32 v[142:143], v[128:129], v[142:143]
	v_max_f32_e32 v139, 0x1e3ce508, v0
	v_pk_mul_f32 v[148:149], v[126:127], v[138:139]
	v_cvt_pk_bf16_f32 v138, v142, v143
	v_lshl_add_u64 v[142:143], s[64:65], 0, v[134:135]
	v_lshlrev_b64 v[134:135], 1, v[132:133]
	v_cvt_pk_bf16_f32 v139, v144, v145
	v_cvt_pk_bf16_f32 v140, v146, v147
	v_cvt_pk_bf16_f32 v141, v148, v149
	v_lshl_add_u64 v[132:133], v[142:143], 0, v[134:135]
	global_load_dwordx4 v[156:159], v[250:251], off offset:256
	global_store_dwordx4 v[132:133], v[138:141], off
	s_nop 1
	v_lshlrev_b32_e32 v0, 16, v160
	v_max_f32_e32 v142, 0x1e3ce508, v0
	v_and_b32_e32 v0, 0xffff0000, v160
	v_max_f32_e32 v143, 0x1e3ce508, v0
	v_lshlrev_b32_e32 v0, 16, v161
	v_max_f32_e32 v138, 0x1e3ce508, v0
	v_and_b32_e32 v0, 0xffff0000, v161
	v_max_f32_e32 v139, 0x1e3ce508, v0
	v_lshlrev_b32_e32 v0, 16, v162
	v_pk_mul_f32 v[144:145], v[98:99], v[138:139]
	v_max_f32_e32 v138, 0x1e3ce508, v0
	v_and_b32_e32 v0, 0xffff0000, v162
	v_max_f32_e32 v139, 0x1e3ce508, v0
	v_lshlrev_b32_e32 v0, 16, v163
	v_pk_mul_f32 v[146:147], v[92:93], v[138:139]
	v_max_f32_e32 v138, 0x1e3ce508, v0
	v_and_b32_e32 v0, 0xffff0000, v163
	v_max_f32_e32 v139, 0x1e3ce508, v0
	v_pk_mul_f32 v[142:143], v[96:97], v[142:143]
	v_pk_mul_f32 v[148:149], v[94:95], v[138:139]
	v_cvt_pk_bf16_f32 v138, v142, v143
	v_cvt_pk_bf16_f32 v139, v144, v145
	v_cvt_pk_bf16_f32 v140, v146, v147
	v_cvt_pk_bf16_f32 v141, v148, v149
	global_store_dwordx4 v[132:133], v[138:141], off offset:256
	s_nop 1
	v_or_b32_e32 v138, 16, v136
	v_ashrrev_i32_e32 v139, 31, v138
	v_lshlrev_b64 v[140:141], 12, v[138:139]
	v_add_co_u32_e32 v138, vcc, s0, v2
	v_lshl_add_u64 v[140:141], s[64:65], 0, v[140:141]
	s_nop 0
	v_addc_co_u32_e32 v139, vcc, 0, v3, vcc
	s_mov_b32 s0, 0x174000
	v_lshlrev_b32_e32 v0, 16, v164
	v_max_f32_e32 v146, 0x1e3ce508, v0
	v_and_b32_e32 v0, 0xffff0000, v164
	v_max_f32_e32 v147, 0x1e3ce508, v0
	v_lshlrev_b32_e32 v0, 16, v165
	v_max_f32_e32 v142, 0x1e3ce508, v0
	v_and_b32_e32 v0, 0xffff0000, v165
	v_max_f32_e32 v143, 0x1e3ce508, v0
	v_lshlrev_b32_e32 v0, 16, v166
	v_pk_mul_f32 v[148:149], v[122:123], v[142:143]
	v_max_f32_e32 v142, 0x1e3ce508, v0
	v_and_b32_e32 v0, 0xffff0000, v166
	v_max_f32_e32 v143, 0x1e3ce508, v0
	v_lshlrev_b32_e32 v0, 16, v167
	v_pk_mul_f32 v[150:151], v[116:117], v[142:143]
	v_max_f32_e32 v142, 0x1e3ce508, v0
	v_and_b32_e32 v0, 0xffff0000, v167
	v_pk_mul_f32 v[146:147], v[120:121], v[146:147]
	v_max_f32_e32 v143, 0x1e3ce508, v0
	v_pk_mul_f32 v[152:153], v[118:119], v[142:143]
	v_cvt_pk_bf16_f32 v142, v146, v147
	v_lshl_add_u64 v[146:147], v[140:141], 0, v[134:135]
	v_cvt_pk_bf16_f32 v143, v148, v149
	v_cvt_pk_bf16_f32 v144, v150, v151
	v_cvt_pk_bf16_f32 v145, v152, v153
	global_store_dwordx4 v[146:147], v[142:145], off
	v_lshlrev_b32_e32 v0, 16, v168
	v_max_f32_e32 v142, 0x1e3ce508, v0
	v_and_b32_e32 v0, 0xffff0000, v168
	v_max_f32_e32 v143, 0x1e3ce508, v0
	v_lshlrev_b32_e32 v0, 16, v169
	v_max_f32_e32 v138, 0x1e3ce508, v0
	v_and_b32_e32 v0, 0xffff0000, v169
	v_max_f32_e32 v139, 0x1e3ce508, v0
	v_lshlrev_b32_e32 v0, 16, v170
	v_pk_mul_f32 v[144:145], v[90:91], v[138:139]
	v_max_f32_e32 v138, 0x1e3ce508, v0
	v_and_b32_e32 v0, 0xffff0000, v170
	v_max_f32_e32 v139, 0x1e3ce508, v0
	v_lshlrev_b32_e32 v0, 16, v171
	v_pk_mul_f32 v[148:149], v[84:85], v[138:139]
	v_max_f32_e32 v138, 0x1e3ce508, v0
	v_and_b32_e32 v0, 0xffff0000, v171
	v_max_f32_e32 v139, 0x1e3ce508, v0
	v_pk_mul_f32 v[142:143], v[88:89], v[142:143]
	v_pk_mul_f32 v[150:151], v[86:87], v[138:139]
	v_cvt_pk_bf16_f32 v138, v142, v143
	v_cvt_pk_bf16_f32 v139, v144, v145
	v_cvt_pk_bf16_f32 v140, v148, v149
	v_cvt_pk_bf16_f32 v141, v150, v151
	global_store_dwordx4 v[146:147], v[138:141], off offset:256
	s_nop 1
	v_or_b32_e32 v138, 32, v136
	v_ashrrev_i32_e32 v139, 31, v138
	v_lshlrev_b64 v[140:141], 12, v[138:139]
	v_add_co_u32_e32 v138, vcc, s4, v2
	v_lshl_add_u64 v[140:141], s[64:65], 0, v[140:141]
	s_nop 0
	v_addc_co_u32_e32 v139, vcc, 0, v3, vcc
	v_or_b32_e32 v136, 48, v136
	v_ashrrev_i32_e32 v137, 31, v136
	v_lshlrev_b32_e32 v0, 16, v172
	v_max_f32_e32 v146, 0x1e3ce508, v0
	v_and_b32_e32 v0, 0xffff0000, v172
	v_max_f32_e32 v147, 0x1e3ce508, v0
	v_lshlrev_b32_e32 v0, 16, v173
	v_max_f32_e32 v142, 0x1e3ce508, v0
	v_and_b32_e32 v0, 0xffff0000, v173
	v_max_f32_e32 v143, 0x1e3ce508, v0
	v_lshlrev_b32_e32 v0, 16, v174
	v_pk_mul_f32 v[148:149], v[114:115], v[142:143]
	v_max_f32_e32 v142, 0x1e3ce508, v0
	v_and_b32_e32 v0, 0xffff0000, v174
	v_max_f32_e32 v143, 0x1e3ce508, v0
	v_lshlrev_b32_e32 v0, 16, v175
	v_pk_mul_f32 v[150:151], v[108:109], v[142:143]
	v_max_f32_e32 v142, 0x1e3ce508, v0
	v_and_b32_e32 v0, 0xffff0000, v175
	v_pk_mul_f32 v[146:147], v[112:113], v[146:147]
	v_max_f32_e32 v143, 0x1e3ce508, v0
	v_pk_mul_f32 v[152:153], v[110:111], v[142:143]
	v_cvt_pk_bf16_f32 v142, v146, v147
	v_lshl_add_u64 v[146:147], v[140:141], 0, v[134:135]
	v_cvt_pk_bf16_f32 v143, v148, v149
	v_cvt_pk_bf16_f32 v144, v150, v151
	v_cvt_pk_bf16_f32 v145, v152, v153
	global_store_dwordx4 v[146:147], v[142:145], off
	v_lshlrev_b32_e32 v0, 16, v176
	v_max_f32_e32 v142, 0x1e3ce508, v0
	v_and_b32_e32 v0, 0xffff0000, v176
	v_max_f32_e32 v143, 0x1e3ce508, v0
	v_lshlrev_b32_e32 v0, 16, v177
	v_max_f32_e32 v138, 0x1e3ce508, v0
	v_and_b32_e32 v0, 0xffff0000, v177
	v_max_f32_e32 v139, 0x1e3ce508, v0
	v_lshlrev_b32_e32 v0, 16, v178
	v_pk_mul_f32 v[144:145], v[82:83], v[138:139]
	v_max_f32_e32 v138, 0x1e3ce508, v0
	v_and_b32_e32 v0, 0xffff0000, v178
	v_max_f32_e32 v139, 0x1e3ce508, v0
	v_lshlrev_b32_e32 v0, 16, v179
	v_pk_mul_f32 v[148:149], v[76:77], v[138:139]
	v_max_f32_e32 v138, 0x1e3ce508, v0
	v_and_b32_e32 v0, 0xffff0000, v179
	v_max_f32_e32 v139, 0x1e3ce508, v0
	v_pk_mul_f32 v[142:143], v[80:81], v[142:143]
	v_pk_mul_f32 v[150:151], v[78:79], v[138:139]
	v_cvt_pk_bf16_f32 v138, v142, v143
	v_cvt_pk_bf16_f32 v139, v144, v145
	v_cvt_pk_bf16_f32 v140, v148, v149
	v_cvt_pk_bf16_f32 v141, v150, v151
	global_store_dwordx4 v[146:147], v[138:141], off offset:256
	s_nop 1
	v_lshlrev_b64 v[138:139], 12, v[136:137]
	v_add_co_u32_e32 v136, vcc, s0, v2
	v_lshl_add_u64 v[138:139], s[64:65], 0, v[138:139]
	s_nop 0
	v_addc_co_u32_e32 v137, vcc, 0, v3, vcc
	v_lshl_add_u64 v[138:139], v[138:139], 0, v[134:135]
	s_mov_b32 s0, 0x3e0000
	v_lshlrev_b32_e32 v0, 16, v180
	v_max_f32_e32 v144, 0x1e3ce508, v0
	v_and_b32_e32 v0, 0xffff0000, v180
	v_max_f32_e32 v145, 0x1e3ce508, v0
	v_lshlrev_b32_e32 v0, 16, v181
	v_max_f32_e32 v140, 0x1e3ce508, v0
	v_and_b32_e32 v0, 0xffff0000, v181
	v_max_f32_e32 v141, 0x1e3ce508, v0
	v_lshlrev_b32_e32 v0, 16, v182
	v_pk_mul_f32 v[146:147], v[106:107], v[140:141]
	v_max_f32_e32 v140, 0x1e3ce508, v0
	v_and_b32_e32 v0, 0xffff0000, v182
	v_max_f32_e32 v141, 0x1e3ce508, v0
	v_lshlrev_b32_e32 v0, 16, v183
	v_pk_mul_f32 v[148:149], v[100:101], v[140:141]
	v_max_f32_e32 v140, 0x1e3ce508, v0
	v_and_b32_e32 v0, 0xffff0000, v183
	v_max_f32_e32 v141, 0x1e3ce508, v0
	v_pk_mul_f32 v[144:145], v[104:105], v[144:145]
	v_pk_mul_f32 v[150:151], v[102:103], v[140:141]
	v_lshlrev_b32_e32 v0, 16, v184
	v_cvt_pk_bf16_f32 v140, v144, v145
	v_cvt_pk_bf16_f32 v141, v146, v147
	v_cvt_pk_bf16_f32 v142, v148, v149
	v_cvt_pk_bf16_f32 v143, v150, v151
	global_store_dwordx4 v[138:139], v[140:143], off
	s_nop 1
	v_max_f32_e32 v140, 0x1e3ce508, v0
	v_and_b32_e32 v0, 0xffff0000, v184
	v_max_f32_e32 v141, 0x1e3ce508, v0
	v_lshlrev_b32_e32 v0, 16, v185
	v_max_f32_e32 v134, 0x1e3ce508, v0
	v_and_b32_e32 v0, 0xffff0000, v185
	v_max_f32_e32 v135, 0x1e3ce508, v0
	v_lshlrev_b32_e32 v0, 16, v186
	v_pk_mul_f32 v[142:143], v[74:75], v[134:135]
	v_max_f32_e32 v134, 0x1e3ce508, v0
	v_and_b32_e32 v0, 0xffff0000, v186
	v_max_f32_e32 v135, 0x1e3ce508, v0
	v_lshlrev_b32_e32 v0, 16, v187
	v_pk_mul_f32 v[144:145], v[68:69], v[134:135]
	v_max_f32_e32 v134, 0x1e3ce508, v0
	v_and_b32_e32 v0, 0xffff0000, v187
	v_max_f32_e32 v135, 0x1e3ce508, v0
	v_pk_mul_f32 v[140:141], v[72:73], v[140:141]
	v_pk_mul_f32 v[146:147], v[70:71], v[134:135]
	v_cvt_pk_bf16_f32 v134, v140, v141
	v_cvt_pk_bf16_f32 v135, v142, v143
	v_cvt_pk_bf16_f32 v136, v144, v145
	v_cvt_pk_bf16_f32 v137, v146, v147
	global_store_dwordx4 v[138:139], v[134:137], off offset:256
	s_nop 1
	v_add_co_u32_e32 v134, vcc, s0, v2
	s_mov_b64 s[0:1], 0x80000
	s_nop 0
	v_addc_co_u32_e32 v135, vcc, 0, v3, vcc
	v_lshlrev_b32_e32 v0, 16, v188
	v_max_f32_e32 v140, 0x1e3ce508, v0
	v_and_b32_e32 v0, 0xffff0000, v188
	v_max_f32_e32 v141, 0x1e3ce508, v0
	v_lshlrev_b32_e32 v0, 16, v189
	v_max_f32_e32 v136, 0x1e3ce508, v0
	v_and_b32_e32 v0, 0xffff0000, v189
	v_max_f32_e32 v137, 0x1e3ce508, v0
	v_lshlrev_b32_e32 v0, 16, v190
	v_pk_mul_f32 v[142:143], v[66:67], v[136:137]
	v_max_f32_e32 v136, 0x1e3ce508, v0
	v_and_b32_e32 v0, 0xffff0000, v190
	v_max_f32_e32 v137, 0x1e3ce508, v0
	v_lshlrev_b32_e32 v0, 16, v191
	v_pk_mul_f32 v[144:145], v[60:61], v[136:137]
	v_max_f32_e32 v136, 0x1e3ce508, v0
	v_and_b32_e32 v0, 0xffff0000, v191
	v_max_f32_e32 v137, 0x1e3ce508, v0
	v_pk_mul_f32 v[140:141], v[64:65], v[140:141]
	v_pk_mul_f32 v[146:147], v[62:63], v[136:137]
	v_cvt_pk_bf16_f32 v137, v142, v143
	v_add_co_u32_e32 v142, vcc, s5, v132
	v_cvt_pk_bf16_f32 v136, v140, v141
	v_cvt_pk_bf16_f32 v138, v144, v145
	v_cvt_pk_bf16_f32 v139, v146, v147
	v_addc_co_u32_e32 v143, vcc, 0, v133, vcc
	global_store_dwordx4 v[142:143], v[136:139], off
	s_nop 1
	v_lshl_add_u64 v[140:141], v[132:133], 0, s[0:1]
	s_mov_b32 s0, 0x45c000
	v_lshlrev_b32_e32 v0, 16, v192
	v_max_f32_e32 v138, 0x1e3ce508, v0
	v_and_b32_e32 v0, 0xffff0000, v192
	v_max_f32_e32 v139, 0x1e3ce508, v0
	v_lshlrev_b32_e32 v0, 16, v193
	v_max_f32_e32 v134, 0x1e3ce508, v0
	v_and_b32_e32 v0, 0xffff0000, v193
	v_max_f32_e32 v135, 0x1e3ce508, v0
	v_lshlrev_b32_e32 v0, 16, v194
	v_pk_mul_f32 v[142:143], v[34:35], v[134:135]
	v_max_f32_e32 v134, 0x1e3ce508, v0
	v_and_b32_e32 v0, 0xffff0000, v194
	v_max_f32_e32 v135, 0x1e3ce508, v0
	v_lshlrev_b32_e32 v0, 16, v195
	v_pk_mul_f32 v[144:145], v[28:29], v[134:135]
	v_max_f32_e32 v134, 0x1e3ce508, v0
	v_and_b32_e32 v0, 0xffff0000, v195
	v_max_f32_e32 v135, 0x1e3ce508, v0
	v_pk_mul_f32 v[138:139], v[32:33], v[138:139]
	v_pk_mul_f32 v[146:147], v[30:31], v[134:135]
	v_cvt_pk_bf16_f32 v134, v138, v139
	v_cvt_pk_bf16_f32 v135, v142, v143
	v_cvt_pk_bf16_f32 v136, v144, v145
	v_cvt_pk_bf16_f32 v137, v146, v147
	global_store_dwordx4 v[140:141], v[134:137], off offset:256
	s_nop 1
	v_add_co_u32_e32 v134, vcc, s0, v2
	s_mov_b64 s[0:1], 0x90000
	s_nop 0
	v_addc_co_u32_e32 v135, vcc, 0, v3, vcc
	v_lshlrev_b32_e32 v0, 16, v210
	v_max_f32_e32 v140, 0x1e3ce508, v0
	v_and_b32_e32 v0, 0xffff0000, v210
	v_max_f32_e32 v141, 0x1e3ce508, v0
	v_lshlrev_b32_e32 v0, 16, v211
	v_max_f32_e32 v136, 0x1e3ce508, v0
	v_and_b32_e32 v0, 0xffff0000, v211
	v_max_f32_e32 v137, 0x1e3ce508, v0
	v_lshlrev_b32_e32 v0, 16, v212
	v_pk_mul_f32 v[142:143], v[58:59], v[136:137]
	v_max_f32_e32 v136, 0x1e3ce508, v0
	v_and_b32_e32 v0, 0xffff0000, v212
	v_max_f32_e32 v137, 0x1e3ce508, v0
	v_lshlrev_b32_e32 v0, 16, v213
	v_pk_mul_f32 v[144:145], v[52:53], v[136:137]
	v_max_f32_e32 v136, 0x1e3ce508, v0
	v_and_b32_e32 v0, 0xffff0000, v213
	v_max_f32_e32 v137, 0x1e3ce508, v0
	v_pk_mul_f32 v[140:141], v[56:57], v[140:141]
	v_pk_mul_f32 v[146:147], v[54:55], v[136:137]
	v_cvt_pk_bf16_f32 v137, v142, v143
	v_add_co_u32_e32 v142, vcc, s6, v132
	v_cvt_pk_bf16_f32 v136, v140, v141
	v_cvt_pk_bf16_f32 v138, v144, v145
	v_cvt_pk_bf16_f32 v139, v146, v147
	v_addc_co_u32_e32 v143, vcc, 0, v133, vcc
	global_store_dwordx4 v[142:143], v[136:139], off
	s_nop 1
	v_lshl_add_u64 v[140:141], v[132:133], 0, s[0:1]
	s_mov_b32 s0, 0x4d8000
	v_lshlrev_b32_e32 v0, 16, v214
	v_max_f32_e32 v138, 0x1e3ce508, v0
	v_and_b32_e32 v0, 0xffff0000, v214
	v_max_f32_e32 v139, 0x1e3ce508, v0
	v_lshlrev_b32_e32 v0, 16, v215
	v_max_f32_e32 v134, 0x1e3ce508, v0
	v_and_b32_e32 v0, 0xffff0000, v215
	v_max_f32_e32 v135, 0x1e3ce508, v0
	v_lshlrev_b32_e32 v0, 16, v216
	v_pk_mul_f32 v[142:143], v[26:27], v[134:135]
	v_max_f32_e32 v134, 0x1e3ce508, v0
	v_and_b32_e32 v0, 0xffff0000, v216
	v_max_f32_e32 v135, 0x1e3ce508, v0
	v_lshlrev_b32_e32 v0, 16, v217
	v_pk_mul_f32 v[144:145], v[20:21], v[134:135]
	v_max_f32_e32 v134, 0x1e3ce508, v0
	v_and_b32_e32 v0, 0xffff0000, v217
	v_max_f32_e32 v135, 0x1e3ce508, v0
	v_pk_mul_f32 v[138:139], v[24:25], v[138:139]
	v_pk_mul_f32 v[146:147], v[22:23], v[134:135]
	v_cvt_pk_bf16_f32 v134, v138, v139
	v_cvt_pk_bf16_f32 v135, v142, v143
	v_cvt_pk_bf16_f32 v136, v144, v145
	v_cvt_pk_bf16_f32 v137, v146, v147
	global_store_dwordx4 v[140:141], v[134:137], off offset:256
	s_nop 1
	v_add_co_u32_e32 v134, vcc, s0, v2
	s_mov_b64 s[0:1], 0xa0000
	s_nop 0
	v_addc_co_u32_e32 v135, vcc, 0, v3, vcc
	v_lshlrev_b32_e32 v0, 16, v228
	v_max_f32_e32 v140, 0x1e3ce508, v0
	v_and_b32_e32 v0, 0xffff0000, v228
	v_max_f32_e32 v141, 0x1e3ce508, v0
	v_lshlrev_b32_e32 v0, 16, v229
	v_max_f32_e32 v136, 0x1e3ce508, v0
	v_and_b32_e32 v0, 0xffff0000, v229
	v_max_f32_e32 v137, 0x1e3ce508, v0
	v_lshlrev_b32_e32 v0, 16, v230
	v_pk_mul_f32 v[142:143], v[50:51], v[136:137]
	v_max_f32_e32 v136, 0x1e3ce508, v0
	v_and_b32_e32 v0, 0xffff0000, v230
	v_max_f32_e32 v137, 0x1e3ce508, v0
	v_lshlrev_b32_e32 v0, 16, v231
	v_pk_mul_f32 v[144:145], v[44:45], v[136:137]
	v_max_f32_e32 v136, 0x1e3ce508, v0
	v_and_b32_e32 v0, 0xffff0000, v231
	v_max_f32_e32 v137, 0x1e3ce508, v0
	v_pk_mul_f32 v[140:141], v[48:49], v[140:141]
	v_pk_mul_f32 v[146:147], v[46:47], v[136:137]
	v_cvt_pk_bf16_f32 v137, v142, v143
	v_add_co_u32_e32 v142, vcc, s7, v132
	v_cvt_pk_bf16_f32 v136, v140, v141
	v_cvt_pk_bf16_f32 v138, v144, v145
	v_cvt_pk_bf16_f32 v139, v146, v147
	v_addc_co_u32_e32 v143, vcc, 0, v133, vcc
	global_store_dwordx4 v[142:143], v[136:139], off
	s_nop 1
	v_lshl_add_u64 v[140:141], v[132:133], 0, s[0:1]
	s_mov_b32 s0, 0x554000
	v_lshlrev_b32_e32 v0, 16, v242
	v_max_f32_e32 v138, 0x1e3ce508, v0
	v_and_b32_e32 v0, 0xffff0000, v242
	v_max_f32_e32 v139, 0x1e3ce508, v0
	v_lshlrev_b32_e32 v0, 16, v243
	v_max_f32_e32 v134, 0x1e3ce508, v0
	v_and_b32_e32 v0, 0xffff0000, v243
	v_max_f32_e32 v135, 0x1e3ce508, v0
	v_lshlrev_b32_e32 v0, 16, v244
	v_pk_mul_f32 v[142:143], v[18:19], v[134:135]
	v_max_f32_e32 v134, 0x1e3ce508, v0
	v_and_b32_e32 v0, 0xffff0000, v244
	v_max_f32_e32 v135, 0x1e3ce508, v0
	v_lshlrev_b32_e32 v0, 16, v245
	v_pk_mul_f32 v[144:145], v[12:13], v[134:135]
	v_max_f32_e32 v134, 0x1e3ce508, v0
	v_and_b32_e32 v0, 0xffff0000, v245
	v_max_f32_e32 v135, 0x1e3ce508, v0
	v_pk_mul_f32 v[138:139], v[16:17], v[138:139]
	v_pk_mul_f32 v[146:147], v[14:15], v[134:135]
	v_cvt_pk_bf16_f32 v134, v138, v139
	v_cvt_pk_bf16_f32 v135, v142, v143
	v_cvt_pk_bf16_f32 v136, v144, v145
	v_cvt_pk_bf16_f32 v137, v146, v147
	global_store_dwordx4 v[140:141], v[134:137], off offset:256
	s_nop 1
	v_add_co_u32_e32 v136, vcc, s0, v2
	s_mov_b64 s[0:1], 0xb0000
	s_nop 0
	v_addc_co_u32_e32 v137, vcc, 0, v3, vcc
	v_lshlrev_b32_e32 v0, 16, v246
	v_max_f32_e32 v134, 0x1e3ce508, v0
	v_and_b32_e32 v0, 0xffff0000, v246
	v_max_f32_e32 v135, 0x1e3ce508, v0
	v_lshlrev_b32_e32 v0, 16, v247
	v_max_f32_e32 v138, 0x1e3ce508, v0
	v_and_b32_e32 v0, 0xffff0000, v247
	v_max_f32_e32 v139, 0x1e3ce508, v0
	v_lshlrev_b32_e32 v0, 16, v248
	v_pk_mul_f32 v[142:143], v[42:43], v[138:139]
	v_max_f32_e32 v138, 0x1e3ce508, v0
	v_and_b32_e32 v0, 0xffff0000, v248
	v_max_f32_e32 v139, 0x1e3ce508, v0
	v_lshlrev_b32_e32 v0, 16, v249
	v_pk_mul_f32 v[144:145], v[36:37], v[138:139]
	v_max_f32_e32 v138, 0x1e3ce508, v0
	v_and_b32_e32 v0, 0xffff0000, v249
	v_pk_mul_f32 v[134:135], v[40:41], v[134:135]
	v_max_f32_e32 v139, 0x1e3ce508, v0
	v_pk_mul_f32 v[146:147], v[38:39], v[138:139]
	v_cvt_pk_bf16_f32 v138, v134, v135
	v_lshl_add_u64 v[134:135], v[132:133], 0, s[0:1]
	v_add_co_u32_e32 v132, vcc, s8, v132
	v_cvt_pk_bf16_f32 v139, v142, v143
	v_cvt_pk_bf16_f32 v140, v144, v145
	v_cvt_pk_bf16_f32 v141, v146, v147
	v_addc_co_u32_e32 v133, vcc, 0, v133, vcc
	global_store_dwordx4 v[132:133], v[138:141], off
	s_nop 1
	s_waitcnt vmcnt(15)
	v_lshlrev_b32_e32 v0, 16, v156
	v_max_f32_e32 v132, 0x1e3ce508, v0
	v_and_b32_e32 v0, 0xffff0000, v156
	v_max_f32_e32 v133, 0x1e3ce508, v0
	v_lshlrev_b32_e32 v0, 16, v157
	v_max_f32_e32 v136, 0x1e3ce508, v0
	v_and_b32_e32 v0, 0xffff0000, v157
	v_max_f32_e32 v137, 0x1e3ce508, v0
	v_lshlrev_b32_e32 v0, 16, v158
	v_pk_mul_f32 v[140:141], v[10:11], v[136:137]
	v_max_f32_e32 v136, 0x1e3ce508, v0
	v_and_b32_e32 v0, 0xffff0000, v158
	v_max_f32_e32 v137, 0x1e3ce508, v0
	v_lshlrev_b32_e32 v0, 16, v159
	v_pk_mul_f32 v[142:143], v[4:5], v[136:137]
	v_max_f32_e32 v136, 0x1e3ce508, v0
	v_and_b32_e32 v0, 0xffff0000, v159
	v_max_f32_e32 v137, 0x1e3ce508, v0
	v_pk_mul_f32 v[132:133], v[8:9], v[132:133]
	v_pk_mul_f32 v[144:145], v[6:7], v[136:137]
	v_cvt_pk_bf16_f32 v136, v132, v133
	v_cvt_pk_bf16_f32 v137, v140, v141
	v_cvt_pk_bf16_f32 v138, v142, v143
	v_cvt_pk_bf16_f32 v139, v144, v145
	global_store_dwordx4 v[134:135], v[136:139], off offset:256
	s_cbranch_execz .LBB0_1240

.LBB0_1240:
	global_load_dwordx4 v[192:195], v[2:3], off
	v_add_co_u32_e32 v132, vcc, 0x1000, v2
	s_mov_b32 s0, 0x174000
	s_nop 0
	v_addc_co_u32_e32 v133, vcc, 0, v3, vcc
	global_load_dwordx4 v[188:191], v[132:133], off
	global_load_dwordx4 v[184:187], v[2:3], off offset:256
	global_load_dwordx4 v[180:183], v[132:133], off offset:256
	v_add_co_u32_e32 v132, vcc, 0x7c000, v2
	s_waitcnt vmcnt(0)
	v_lshlrev_b32_e32 v0, 16, v192
	v_max_f32_e32 v210, 0x1e3ce508, v0
	v_addc_co_u32_e32 v133, vcc, 0, v3, vcc
	v_lshlrev_b32_e32 v0, 16, v188
	v_max_f32_e32 v0, 0x1e3ce508, v0
	v_rcp_f32_e32 v212, v0
	v_and_b32_e32 v0, 0xffff0000, v192
	global_load_dwordx4 v[172:175], v[132:133], off
	v_max_f32_e32 v211, 0x1e3ce508, v0
	v_and_b32_e32 v0, 0xffff0000, v188
	v_add_co_u32_e32 v134, vcc, 0x7d000, v2
	s_nop 0
	v_addc_co_u32_e32 v135, vcc, 0, v3, vcc
	v_max_f32_e32 v0, 0x1e3ce508, v0
	global_load_dwordx4 v[176:179], v[134:135], off
	global_load_dwordx4 v[168:171], v[132:133], off offset:256
	global_load_dwordx4 v[164:167], v[134:135], off offset:256
	v_rcp_f32_e32 v213, v0
	v_lshlrev_b32_e32 v0, 16, v193
	v_max_f32_e32 v192, 0x1e3ce508, v0
	v_lshlrev_b32_e32 v0, 16, v189
	v_max_f32_e32 v0, 0x1e3ce508, v0
	v_rcp_f32_e32 v188, v0
	v_and_b32_e32 v0, 0xffff0000, v193
	v_max_f32_e32 v193, 0x1e3ce508, v0
	v_and_b32_e32 v0, 0xffff0000, v189
	v_max_f32_e32 v0, 0x1e3ce508, v0
	v_rcp_f32_e32 v189, v0
	v_lshlrev_b32_e32 v0, 16, v194
	v_add_co_u32_e32 v132, vcc, s4, v2
	v_pk_mul_f32 v[188:189], v[192:193], v[188:189]
	s_nop 0
	v_addc_co_u32_e32 v133, vcc, 0, v3, vcc
	v_pk_mul_f32 v[130:131], v[130:131], v[188:189]
	v_max_f32_e32 v188, 0x1e3ce508, v0
	v_lshlrev_b32_e32 v0, 16, v190
	v_max_f32_e32 v0, 0x1e3ce508, v0
	v_rcp_f32_e32 v192, v0
	v_and_b32_e32 v0, 0xffff0000, v194
	v_max_f32_e32 v189, 0x1e3ce508, v0
	v_and_b32_e32 v0, 0xffff0000, v190
	v_max_f32_e32 v0, 0x1e3ce508, v0
	v_rcp_f32_e32 v193, v0
	v_lshlrev_b32_e32 v0, 16, v195
	v_max_f32_e32 v194, 0x1e3ce508, v0
	v_lshlrev_b32_e32 v0, 16, v191
	v_max_f32_e32 v0, 0x1e3ce508, v0
	v_rcp_f32_e32 v190, v0
	v_and_b32_e32 v0, 0xffff0000, v195
	v_max_f32_e32 v195, 0x1e3ce508, v0
	v_and_b32_e32 v0, 0xffff0000, v191
	v_max_f32_e32 v0, 0x1e3ce508, v0
	v_rcp_f32_e32 v191, v0
	v_lshlrev_b32_e32 v0, 16, v184
	v_pk_mul_f32 v[188:189], v[188:189], v[192:193]
	v_pk_mul_f32 v[124:125], v[124:125], v[188:189]
	v_max_f32_e32 v188, 0x1e3ce508, v0
	v_lshlrev_b32_e32 v0, 16, v180
	v_pk_mul_f32 v[190:191], v[194:195], v[190:191]
	v_max_f32_e32 v0, 0x1e3ce508, v0
	v_pk_mul_f32 v[126:127], v[126:127], v[190:191]
	v_rcp_f32_e32 v190, v0
	v_and_b32_e32 v0, 0xffff0000, v184
	v_max_f32_e32 v189, 0x1e3ce508, v0
	v_and_b32_e32 v0, 0xffff0000, v180
	v_max_f32_e32 v0, 0x1e3ce508, v0
	v_rcp_f32_e32 v191, v0
	v_lshlrev_b32_e32 v0, 16, v185
	v_max_f32_e32 v184, 0x1e3ce508, v0
	v_lshlrev_b32_e32 v0, 16, v181
	v_max_f32_e32 v0, 0x1e3ce508, v0
	v_rcp_f32_e32 v180, v0
	v_and_b32_e32 v0, 0xffff0000, v185
	v_max_f32_e32 v185, 0x1e3ce508, v0
	v_and_b32_e32 v0, 0xffff0000, v181
	v_max_f32_e32 v0, 0x1e3ce508, v0
	v_rcp_f32_e32 v181, v0
	v_lshlrev_b32_e32 v0, 16, v186
	global_load_dwordx4 v[156:159], v[132:133], off
	v_pk_mul_f32 v[180:181], v[184:185], v[180:181]
	v_add_co_u32_e32 v134, vcc, 0xf9000, v2
	v_pk_mul_f32 v[98:99], v[98:99], v[180:181]
	v_max_f32_e32 v180, 0x1e3ce508, v0
	v_lshlrev_b32_e32 v0, 16, v182
	v_max_f32_e32 v0, 0x1e3ce508, v0
	v_rcp_f32_e32 v184, v0
	v_and_b32_e32 v0, 0xffff0000, v186
	v_max_f32_e32 v181, 0x1e3ce508, v0
	v_and_b32_e32 v0, 0xffff0000, v182
	v_max_f32_e32 v0, 0x1e3ce508, v0
	v_rcp_f32_e32 v185, v0
	v_lshlrev_b32_e32 v0, 16, v187
	v_max_f32_e32 v186, 0x1e3ce508, v0
	v_lshlrev_b32_e32 v0, 16, v183
	v_max_f32_e32 v0, 0x1e3ce508, v0
	v_rcp_f32_e32 v182, v0
	v_and_b32_e32 v0, 0xffff0000, v187
	v_max_f32_e32 v187, 0x1e3ce508, v0
	v_and_b32_e32 v0, 0xffff0000, v183
	v_max_f32_e32 v0, 0x1e3ce508, v0
	v_rcp_f32_e32 v183, v0
	s_waitcnt vmcnt(0)
	v_lshlrev_b32_e32 v0, 16, v172
	v_pk_mul_f32 v[180:181], v[180:181], v[184:185]
	v_pk_mul_f32 v[92:93], v[92:93], v[180:181]
	v_max_f32_e32 v180, 0x1e3ce508, v0
	v_lshlrev_b32_e32 v0, 16, v176
	v_pk_mul_f32 v[182:183], v[186:187], v[182:183]
	v_max_f32_e32 v0, 0x1e3ce508, v0
	v_pk_mul_f32 v[94:95], v[94:95], v[182:183]
	v_rcp_f32_e32 v182, v0
	v_and_b32_e32 v0, 0xffff0000, v172
	v_max_f32_e32 v181, 0x1e3ce508, v0
	v_and_b32_e32 v0, 0xffff0000, v176
	v_addc_co_u32_e32 v135, vcc, 0, v3, vcc
	v_max_f32_e32 v0, 0x1e3ce508, v0
	global_load_dwordx4 v[160:163], v[134:135], off
	global_load_dwordx4 v[152:155], v[132:133], off offset:256
	global_load_dwordx4 v[148:151], v[134:135], off offset:256
	v_rcp_f32_e32 v183, v0
	v_lshlrev_b32_e32 v0, 16, v173
	v_max_f32_e32 v172, 0x1e3ce508, v0
	v_lshlrev_b32_e32 v0, 16, v177
	v_max_f32_e32 v0, 0x1e3ce508, v0
	v_rcp_f32_e32 v176, v0
	v_and_b32_e32 v0, 0xffff0000, v173
	v_max_f32_e32 v173, 0x1e3ce508, v0
	v_and_b32_e32 v0, 0xffff0000, v177
	v_max_f32_e32 v0, 0x1e3ce508, v0
	v_rcp_f32_e32 v177, v0
	v_lshlrev_b32_e32 v0, 16, v174
	v_add_co_u32_e32 v132, vcc, s0, v2
	v_pk_mul_f32 v[172:173], v[172:173], v[176:177]
	s_nop 0
	v_addc_co_u32_e32 v133, vcc, 0, v3, vcc
	v_pk_mul_f32 v[122:123], v[122:123], v[172:173]
	v_max_f32_e32 v172, 0x1e3ce508, v0
	v_lshlrev_b32_e32 v0, 16, v178
	v_max_f32_e32 v0, 0x1e3ce508, v0
	v_rcp_f32_e32 v176, v0
	v_and_b32_e32 v0, 0xffff0000, v174
	v_max_f32_e32 v173, 0x1e3ce508, v0
	v_and_b32_e32 v0, 0xffff0000, v178
	v_max_f32_e32 v0, 0x1e3ce508, v0
	v_rcp_f32_e32 v177, v0
	v_lshlrev_b32_e32 v0, 16, v175
	v_max_f32_e32 v174, 0x1e3ce508, v0
	v_lshlrev_b32_e32 v0, 16, v179
	v_max_f32_e32 v0, 0x1e3ce508, v0
	v_rcp_f32_e32 v178, v0
	v_and_b32_e32 v0, 0xffff0000, v175
	v_max_f32_e32 v175, 0x1e3ce508, v0
	v_and_b32_e32 v0, 0xffff0000, v179
	v_max_f32_e32 v0, 0x1e3ce508, v0
	v_rcp_f32_e32 v179, v0
	v_lshlrev_b32_e32 v0, 16, v168
	v_pk_mul_f32 v[172:173], v[172:173], v[176:177]
	v_pk_mul_f32 v[116:117], v[116:117], v[172:173]
	v_max_f32_e32 v172, 0x1e3ce508, v0
	v_lshlrev_b32_e32 v0, 16, v164
	v_pk_mul_f32 v[174:175], v[174:175], v[178:179]
	v_max_f32_e32 v0, 0x1e3ce508, v0
	v_pk_mul_f32 v[118:119], v[118:119], v[174:175]
	v_rcp_f32_e32 v174, v0
	v_and_b32_e32 v0, 0xffff0000, v168
	v_max_f32_e32 v173, 0x1e3ce508, v0
	v_and_b32_e32 v0, 0xffff0000, v164
	v_max_f32_e32 v0, 0x1e3ce508, v0
	v_rcp_f32_e32 v175, v0
	v_lshlrev_b32_e32 v0, 16, v169
	v_max_f32_e32 v168, 0x1e3ce508, v0
	v_lshlrev_b32_e32 v0, 16, v165
	v_max_f32_e32 v0, 0x1e3ce508, v0
	v_rcp_f32_e32 v164, v0
	v_and_b32_e32 v0, 0xffff0000, v169
	v_max_f32_e32 v169, 0x1e3ce508, v0
	v_and_b32_e32 v0, 0xffff0000, v165
	v_max_f32_e32 v0, 0x1e3ce508, v0
	v_rcp_f32_e32 v165, v0
	v_lshlrev_b32_e32 v0, 16, v170
	global_load_dwordx4 v[140:143], v[132:133], off
	v_pk_mul_f32 v[164:165], v[168:169], v[164:165]
	v_add_co_u32_e32 v136, vcc, 0x175000, v2
	v_pk_mul_f32 v[90:91], v[90:91], v[164:165]
	v_max_f32_e32 v164, 0x1e3ce508, v0
	v_lshlrev_b32_e32 v0, 16, v166
	v_max_f32_e32 v0, 0x1e3ce508, v0
	v_rcp_f32_e32 v168, v0
	v_and_b32_e32 v0, 0xffff0000, v170
	v_max_f32_e32 v165, 0x1e3ce508, v0
	v_and_b32_e32 v0, 0xffff0000, v166
	v_max_f32_e32 v0, 0x1e3ce508, v0
	v_rcp_f32_e32 v169, v0
	v_lshlrev_b32_e32 v0, 16, v171
	v_max_f32_e32 v170, 0x1e3ce508, v0
	v_lshlrev_b32_e32 v0, 16, v167
	v_max_f32_e32 v0, 0x1e3ce508, v0
	v_rcp_f32_e32 v166, v0
	v_and_b32_e32 v0, 0xffff0000, v171
	v_max_f32_e32 v171, 0x1e3ce508, v0
	v_and_b32_e32 v0, 0xffff0000, v167
	v_max_f32_e32 v0, 0x1e3ce508, v0
	v_rcp_f32_e32 v167, v0
	v_lshlrev_b32_e32 v0, 16, v156
	v_pk_mul_f32 v[164:165], v[164:165], v[168:169]
	v_pk_mul_f32 v[84:85], v[84:85], v[164:165]
	v_max_f32_e32 v164, 0x1e3ce508, v0
	s_waitcnt vmcnt(0)
	v_lshlrev_b32_e32 v0, 16, v160
	v_pk_mul_f32 v[166:167], v[170:171], v[166:167]
	v_max_f32_e32 v0, 0x1e3ce508, v0
	v_pk_mul_f32 v[86:87], v[86:87], v[166:167]
	v_rcp_f32_e32 v166, v0
	v_and_b32_e32 v0, 0xffff0000, v156
	v_max_f32_e32 v165, 0x1e3ce508, v0
	v_and_b32_e32 v0, 0xffff0000, v160
	v_addc_co_u32_e32 v137, vcc, 0, v3, vcc
	v_max_f32_e32 v0, 0x1e3ce508, v0
	global_load_dwordx4 v[144:147], v[136:137], off
	s_nop 0
	global_load_dwordx4 v[132:135], v[132:133], off offset:256
	s_nop 0
	global_load_dwordx4 v[136:139], v[136:137], off offset:256
	v_rcp_f32_e32 v167, v0
	v_lshlrev_b32_e32 v0, 16, v157
	v_max_f32_e32 v156, 0x1e3ce508, v0
	v_lshlrev_b32_e32 v0, 16, v161
	v_max_f32_e32 v0, 0x1e3ce508, v0
	v_rcp_f32_e32 v160, v0
	v_and_b32_e32 v0, 0xffff0000, v157
	v_max_f32_e32 v157, 0x1e3ce508, v0
	v_and_b32_e32 v0, 0xffff0000, v161
	v_max_f32_e32 v0, 0x1e3ce508, v0
	v_rcp_f32_e32 v161, v0
	v_lshlrev_b32_e32 v0, 16, v158
	s_mov_b32 s0, 0x3e0000
	v_pk_mul_f32 v[156:157], v[156:157], v[160:161]
	v_pk_mul_f32 v[188:189], v[188:189], v[190:191]
	v_pk_mul_f32 v[114:115], v[114:115], v[156:157]
	v_max_f32_e32 v156, 0x1e3ce508, v0
	v_lshlrev_b32_e32 v0, 16, v162
	v_max_f32_e32 v0, 0x1e3ce508, v0
	v_rcp_f32_e32 v160, v0
	v_and_b32_e32 v0, 0xffff0000, v158
	v_max_f32_e32 v157, 0x1e3ce508, v0
	v_and_b32_e32 v0, 0xffff0000, v162
	v_max_f32_e32 v0, 0x1e3ce508, v0
	v_rcp_f32_e32 v161, v0
	v_lshlrev_b32_e32 v0, 16, v159
	v_max_f32_e32 v158, 0x1e3ce508, v0
	v_lshlrev_b32_e32 v0, 16, v163
	v_max_f32_e32 v0, 0x1e3ce508, v0
	v_rcp_f32_e32 v162, v0
	v_and_b32_e32 v0, 0xffff0000, v159
	v_max_f32_e32 v159, 0x1e3ce508, v0
	v_and_b32_e32 v0, 0xffff0000, v163
	v_max_f32_e32 v0, 0x1e3ce508, v0
	v_rcp_f32_e32 v163, v0
	v_lshlrev_b32_e32 v0, 16, v152
	v_pk_mul_f32 v[156:157], v[156:157], v[160:161]
	v_pk_mul_f32 v[108:109], v[108:109], v[156:157]
	v_max_f32_e32 v156, 0x1e3ce508, v0
	v_lshlrev_b32_e32 v0, 16, v148
	v_pk_mul_f32 v[158:159], v[158:159], v[162:163]
	v_max_f32_e32 v0, 0x1e3ce508, v0
	v_pk_mul_f32 v[110:111], v[110:111], v[158:159]
	v_rcp_f32_e32 v158, v0
	v_and_b32_e32 v0, 0xffff0000, v152
	v_max_f32_e32 v157, 0x1e3ce508, v0
	v_and_b32_e32 v0, 0xffff0000, v148
	v_max_f32_e32 v0, 0x1e3ce508, v0
	v_rcp_f32_e32 v159, v0
	v_lshlrev_b32_e32 v0, 16, v153
	v_max_f32_e32 v152, 0x1e3ce508, v0
	v_lshlrev_b32_e32 v0, 16, v149
	v_max_f32_e32 v0, 0x1e3ce508, v0
	v_rcp_f32_e32 v148, v0
	v_and_b32_e32 v0, 0xffff0000, v153
	v_max_f32_e32 v153, 0x1e3ce508, v0
	v_and_b32_e32 v0, 0xffff0000, v149
	v_max_f32_e32 v0, 0x1e3ce508, v0
	v_rcp_f32_e32 v149, v0
	v_lshlrev_b32_e32 v0, 16, v154
	v_pk_mul_f32 v[172:173], v[172:173], v[174:175]
	v_pk_mul_f32 v[148:149], v[152:153], v[148:149]
	v_pk_mul_f32 v[96:97], v[96:97], v[188:189]
	v_pk_mul_f32 v[82:83], v[82:83], v[148:149]
	v_max_f32_e32 v148, 0x1e3ce508, v0
	v_lshlrev_b32_e32 v0, 16, v150
	v_max_f32_e32 v0, 0x1e3ce508, v0
	v_rcp_f32_e32 v152, v0
	v_and_b32_e32 v0, 0xffff0000, v154
	v_max_f32_e32 v149, 0x1e3ce508, v0
	v_and_b32_e32 v0, 0xffff0000, v150
	v_max_f32_e32 v0, 0x1e3ce508, v0
	v_rcp_f32_e32 v153, v0
	v_lshlrev_b32_e32 v0, 16, v155
	v_max_f32_e32 v154, 0x1e3ce508, v0
	v_lshlrev_b32_e32 v0, 16, v151
	v_max_f32_e32 v0, 0x1e3ce508, v0
	v_rcp_f32_e32 v150, v0
	v_and_b32_e32 v0, 0xffff0000, v155
	v_max_f32_e32 v155, 0x1e3ce508, v0
	v_and_b32_e32 v0, 0xffff0000, v151
	v_max_f32_e32 v0, 0x1e3ce508, v0
	v_rcp_f32_e32 v151, v0
	v_lshlrev_b32_e32 v0, 16, v140
	v_pk_mul_f32 v[148:149], v[148:149], v[152:153]
	v_pk_mul_f32 v[76:77], v[76:77], v[148:149]
	v_max_f32_e32 v148, 0x1e3ce508, v0
	s_waitcnt vmcnt(0)
	v_lshlrev_b32_e32 v0, 16, v144
	v_pk_mul_f32 v[150:151], v[154:155], v[150:151]
	v_max_f32_e32 v0, 0x1e3ce508, v0
	v_pk_mul_f32 v[78:79], v[78:79], v[150:151]
	v_rcp_f32_e32 v150, v0
	v_and_b32_e32 v0, 0xffff0000, v140
	v_max_f32_e32 v149, 0x1e3ce508, v0
	v_and_b32_e32 v0, 0xffff0000, v144
	v_max_f32_e32 v0, 0x1e3ce508, v0
	v_rcp_f32_e32 v151, v0
	v_lshlrev_b32_e32 v0, 16, v141
	v_max_f32_e32 v140, 0x1e3ce508, v0
	v_lshlrev_b32_e32 v0, 16, v145
	v_max_f32_e32 v0, 0x1e3ce508, v0
	v_rcp_f32_e32 v144, v0
	v_and_b32_e32 v0, 0xffff0000, v141
	v_max_f32_e32 v141, 0x1e3ce508, v0
	v_and_b32_e32 v0, 0xffff0000, v145
	v_max_f32_e32 v0, 0x1e3ce508, v0
	v_rcp_f32_e32 v145, v0
	v_lshlrev_b32_e32 v0, 16, v142
	v_pk_mul_f32 v[88:89], v[88:89], v[172:173]
	v_pk_mul_f32 v[140:141], v[140:141], v[144:145]
	v_pk_mul_f32 v[180:181], v[180:181], v[182:183]
	v_pk_mul_f32 v[106:107], v[106:107], v[140:141]
	v_max_f32_e32 v140, 0x1e3ce508, v0
	v_lshlrev_b32_e32 v0, 16, v146
	v_max_f32_e32 v0, 0x1e3ce508, v0
	v_rcp_f32_e32 v144, v0
	v_and_b32_e32 v0, 0xffff0000, v142
	v_max_f32_e32 v141, 0x1e3ce508, v0
	v_and_b32_e32 v0, 0xffff0000, v146
	v_max_f32_e32 v0, 0x1e3ce508, v0
	v_rcp_f32_e32 v145, v0
	v_lshlrev_b32_e32 v0, 16, v143
	v_max_f32_e32 v142, 0x1e3ce508, v0
	v_lshlrev_b32_e32 v0, 16, v147
	v_max_f32_e32 v0, 0x1e3ce508, v0
	v_rcp_f32_e32 v146, v0
	v_and_b32_e32 v0, 0xffff0000, v143
	v_max_f32_e32 v143, 0x1e3ce508, v0
	v_and_b32_e32 v0, 0xffff0000, v147
	v_max_f32_e32 v0, 0x1e3ce508, v0
	v_rcp_f32_e32 v147, v0
	v_lshlrev_b32_e32 v0, 16, v132
	v_pk_mul_f32 v[140:141], v[140:141], v[144:145]
	v_pk_mul_f32 v[100:101], v[100:101], v[140:141]
	v_max_f32_e32 v140, 0x1e3ce508, v0
	v_lshlrev_b32_e32 v0, 16, v136
	v_pk_mul_f32 v[142:143], v[142:143], v[146:147]
	v_max_f32_e32 v0, 0x1e3ce508, v0
	v_pk_mul_f32 v[102:103], v[102:103], v[142:143]
	v_rcp_f32_e32 v142, v0
	v_and_b32_e32 v0, 0xffff0000, v132
	v_max_f32_e32 v141, 0x1e3ce508, v0
	v_and_b32_e32 v0, 0xffff0000, v136
	v_max_f32_e32 v0, 0x1e3ce508, v0
	v_rcp_f32_e32 v143, v0
	v_lshlrev_b32_e32 v0, 16, v133
	v_max_f32_e32 v132, 0x1e3ce508, v0
	v_lshlrev_b32_e32 v0, 16, v137
	v_max_f32_e32 v0, 0x1e3ce508, v0
	v_rcp_f32_e32 v136, v0
	v_and_b32_e32 v0, 0xffff0000, v133
	v_max_f32_e32 v133, 0x1e3ce508, v0
	v_and_b32_e32 v0, 0xffff0000, v137
	v_max_f32_e32 v0, 0x1e3ce508, v0
	v_rcp_f32_e32 v137, v0
	v_lshlrev_b32_e32 v0, 16, v134
	v_pk_mul_f32 v[164:165], v[164:165], v[166:167]
	v_pk_mul_f32 v[132:133], v[132:133], v[136:137]
	v_pk_mul_f32 v[120:121], v[120:121], v[180:181]
	v_pk_mul_f32 v[74:75], v[74:75], v[132:133]
	v_max_f32_e32 v132, 0x1e3ce508, v0
	v_lshlrev_b32_e32 v0, 16, v138
	v_max_f32_e32 v0, 0x1e3ce508, v0
	v_rcp_f32_e32 v136, v0
	v_and_b32_e32 v0, 0xffff0000, v134
	v_max_f32_e32 v133, 0x1e3ce508, v0
	v_and_b32_e32 v0, 0xffff0000, v138
	v_max_f32_e32 v0, 0x1e3ce508, v0
	v_rcp_f32_e32 v137, v0
	v_lshlrev_b32_e32 v0, 16, v135
	v_max_f32_e32 v134, 0x1e3ce508, v0
	v_lshlrev_b32_e32 v0, 16, v139
	v_max_f32_e32 v0, 0x1e3ce508, v0
	v_rcp_f32_e32 v138, v0
	v_and_b32_e32 v0, 0xffff0000, v135
	v_max_f32_e32 v135, 0x1e3ce508, v0
	v_and_b32_e32 v0, 0xffff0000, v139
	v_max_f32_e32 v0, 0x1e3ce508, v0
	v_rcp_f32_e32 v139, v0
	v_pk_mul_f32 v[132:133], v[132:133], v[136:137]
	v_pk_mul_f32 v[112:113], v[112:113], v[164:165]
	v_pk_mul_f32 v[68:69], v[68:69], v[132:133]
	v_add_co_u32_e32 v132, vcc, s0, v2
	v_pk_mul_f32 v[134:135], v[134:135], v[138:139]
	s_nop 0
	v_addc_co_u32_e32 v133, vcc, 0, v3, vcc
	s_mov_b32 s0, 0x3e1000
	v_pk_mul_f32 v[70:71], v[70:71], v[134:135]
	v_add_co_u32_e32 v134, vcc, s0, v2
	s_mov_b32 s0, 0x45c000
	s_nop 0
	v_addc_co_u32_e32 v135, vcc, 0, v3, vcc
	global_load_dwordx4 v[192:195], v[134:135], off offset:-4096
	global_load_dwordx4 v[188:191], v[134:135], off
	global_load_dwordx4 v[176:179], v[132:133], off offset:256
	global_load_dwordx4 v[172:175], v[134:135], off offset:256
	v_add_co_u32_e32 v132, vcc, s0, v2
	s_mov_b32 s0, 0x45d000
	s_nop 0
	v_addc_co_u32_e32 v133, vcc, 0, v3, vcc
	v_add_co_u32_e32 v134, vcc, s0, v2
	s_mov_b32 s0, 0x4d8000
	s_nop 0
	v_addc_co_u32_e32 v135, vcc, 0, v3, vcc
	global_load_dwordx4 v[184:187], v[134:135], off offset:-4096
	global_load_dwordx4 v[180:183], v[134:135], off
	global_load_dwordx4 v[168:171], v[132:133], off offset:256
	global_load_dwordx4 v[164:167], v[134:135], off offset:256
	v_add_co_u32_e32 v132, vcc, s0, v2
	s_mov_b32 s0, 0x4d9000
	s_nop 0
	v_addc_co_u32_e32 v133, vcc, 0, v3, vcc
	v_add_co_u32_e32 v134, vcc, s0, v2
	v_pk_mul_f32 v[156:157], v[156:157], v[158:159]
	v_pk_mul_f32 v[148:149], v[148:149], v[150:151]
	v_addc_co_u32_e32 v135, vcc, 0, v3, vcc
	s_mov_b32 s0, 0x554000
	v_pk_mul_f32 v[80:81], v[80:81], v[156:157]
	v_pk_mul_f32 v[104:105], v[104:105], v[148:149]
	global_load_dwordx4 v[160:163], v[134:135], off offset:-4096
	global_load_dwordx4 v[156:159], v[134:135], off
	global_load_dwordx4 v[152:155], v[132:133], off offset:256
	global_load_dwordx4 v[148:151], v[134:135], off offset:256
	v_add_co_u32_e32 v132, vcc, s0, v2
	s_mov_b32 s0, 0x555000
	s_nop 0
	v_addc_co_u32_e32 v133, vcc, 0, v3, vcc
	v_add_co_u32_e32 v2, vcc, s0, v2
	v_pk_mul_f32 v[140:141], v[140:141], v[142:143]
	s_nop 0
	v_addc_co_u32_e32 v3, vcc, 0, v3, vcc
	v_pk_mul_f32 v[72:73], v[72:73], v[140:141]
	global_load_dwordx4 v[144:147], v[2:3], off offset:-4096
	global_load_dwordx4 v[140:143], v[2:3], off
	global_load_dwordx4 v[136:139], v[132:133], off offset:256
	s_nop 0
	global_load_dwordx4 v[132:135], v[2:3], off offset:256
	v_pk_mul_f32 v[210:211], v[210:211], v[212:213]
	s_waitcnt vmcnt(0)
	v_lshlrev_b32_e32 v0, 16, v192
	v_max_f32_e32 v2, 0x1e3ce508, v0
	v_lshlrev_b32_e32 v0, 16, v188
	v_max_f32_e32 v0, 0x1e3ce508, v0
	v_pk_mul_f32 v[128:129], v[128:129], v[210:211]
	v_rcp_f32_e32 v210, v0
	v_and_b32_e32 v0, 0xffff0000, v192
	v_max_f32_e32 v3, 0x1e3ce508, v0
	v_and_b32_e32 v0, 0xffff0000, v188
	v_max_f32_e32 v0, 0x1e3ce508, v0
	v_rcp_f32_e32 v211, v0
	v_lshlrev_b32_e32 v0, 16, v193
	v_max_f32_e32 v192, 0x1e3ce508, v0
	v_lshlrev_b32_e32 v0, 16, v189
	v_max_f32_e32 v0, 0x1e3ce508, v0
	v_rcp_f32_e32 v188, v0
	v_and_b32_e32 v0, 0xffff0000, v193
	v_max_f32_e32 v193, 0x1e3ce508, v0
	v_and_b32_e32 v0, 0xffff0000, v189
	v_max_f32_e32 v0, 0x1e3ce508, v0
	v_rcp_f32_e32 v189, v0
	v_lshlrev_b32_e32 v0, 16, v194
	v_pk_mul_f32 v[2:3], v[2:3], v[210:211]
	v_pk_mul_f32 v[64:65], v[64:65], v[2:3]
	v_max_f32_e32 v2, 0x1e3ce508, v0
	v_lshlrev_b32_e32 v0, 16, v190
	v_pk_mul_f32 v[188:189], v[192:193], v[188:189]
	v_max_f32_e32 v0, 0x1e3ce508, v0
	v_pk_mul_f32 v[66:67], v[66:67], v[188:189]
	v_rcp_f32_e32 v188, v0
	v_and_b32_e32 v0, 0xffff0000, v194
	v_max_f32_e32 v3, 0x1e3ce508, v0
	v_and_b32_e32 v0, 0xffff0000, v190
	v_max_f32_e32 v0, 0x1e3ce508, v0
	v_rcp_f32_e32 v189, v0
	v_lshlrev_b32_e32 v0, 16, v195
	v_max_f32_e32 v192, 0x1e3ce508, v0
	v_lshlrev_b32_e32 v0, 16, v191
	v_max_f32_e32 v0, 0x1e3ce508, v0
	v_rcp_f32_e32 v190, v0
	v_and_b32_e32 v0, 0xffff0000, v195
	v_max_f32_e32 v193, 0x1e3ce508, v0
	v_and_b32_e32 v0, 0xffff0000, v191
	v_max_f32_e32 v0, 0x1e3ce508, v0
	v_rcp_f32_e32 v191, v0
	v_lshlrev_b32_e32 v0, 16, v176
	v_pk_mul_f32 v[2:3], v[2:3], v[188:189]
	v_pk_mul_f32 v[60:61], v[60:61], v[2:3]
	v_max_f32_e32 v2, 0x1e3ce508, v0
	v_lshlrev_b32_e32 v0, 16, v172
	v_pk_mul_f32 v[188:189], v[192:193], v[190:191]
	v_max_f32_e32 v0, 0x1e3ce508, v0
	v_pk_mul_f32 v[62:63], v[62:63], v[188:189]
	v_rcp_f32_e32 v188, v0
	v_and_b32_e32 v0, 0xffff0000, v176
	v_max_f32_e32 v3, 0x1e3ce508, v0
	v_and_b32_e32 v0, 0xffff0000, v172
	v_max_f32_e32 v0, 0x1e3ce508, v0
	v_rcp_f32_e32 v189, v0
	v_lshlrev_b32_e32 v0, 16, v177
	v_max_f32_e32 v176, 0x1e3ce508, v0
	v_lshlrev_b32_e32 v0, 16, v173
	v_max_f32_e32 v0, 0x1e3ce508, v0
	v_rcp_f32_e32 v172, v0
	v_and_b32_e32 v0, 0xffff0000, v177
	v_max_f32_e32 v177, 0x1e3ce508, v0
	v_and_b32_e32 v0, 0xffff0000, v173
	v_max_f32_e32 v0, 0x1e3ce508, v0
	v_rcp_f32_e32 v173, v0
	v_lshlrev_b32_e32 v0, 16, v178
	v_pk_mul_f32 v[2:3], v[2:3], v[188:189]
	v_pk_mul_f32 v[32:33], v[32:33], v[2:3]
	v_max_f32_e32 v2, 0x1e3ce508, v0
	v_lshlrev_b32_e32 v0, 16, v174
	v_pk_mul_f32 v[172:173], v[176:177], v[172:173]
	v_max_f32_e32 v0, 0x1e3ce508, v0
	v_pk_mul_f32 v[34:35], v[34:35], v[172:173]
	v_rcp_f32_e32 v172, v0
	v_and_b32_e32 v0, 0xffff0000, v178
	v_max_f32_e32 v3, 0x1e3ce508, v0
	v_and_b32_e32 v0, 0xffff0000, v174
	v_max_f32_e32 v0, 0x1e3ce508, v0
	v_rcp_f32_e32 v173, v0
	v_lshlrev_b32_e32 v0, 16, v179
	v_max_f32_e32 v176, 0x1e3ce508, v0
	v_lshlrev_b32_e32 v0, 16, v175
	v_max_f32_e32 v0, 0x1e3ce508, v0
	v_rcp_f32_e32 v174, v0
	v_and_b32_e32 v0, 0xffff0000, v179
	v_max_f32_e32 v177, 0x1e3ce508, v0
	v_and_b32_e32 v0, 0xffff0000, v175
	v_max_f32_e32 v0, 0x1e3ce508, v0
	v_rcp_f32_e32 v175, v0
	v_lshlrev_b32_e32 v0, 16, v184
	v_pk_mul_f32 v[2:3], v[2:3], v[172:173]
	v_pk_mul_f32 v[28:29], v[28:29], v[2:3]
	v_max_f32_e32 v2, 0x1e3ce508, v0
	v_lshlrev_b32_e32 v0, 16, v180
	v_pk_mul_f32 v[172:173], v[176:177], v[174:175]
	v_max_f32_e32 v0, 0x1e3ce508, v0
	v_pk_mul_f32 v[30:31], v[30:31], v[172:173]
	v_rcp_f32_e32 v172, v0
	v_and_b32_e32 v0, 0xffff0000, v184
	v_max_f32_e32 v3, 0x1e3ce508, v0
	v_and_b32_e32 v0, 0xffff0000, v180
	v_max_f32_e32 v0, 0x1e3ce508, v0
	v_rcp_f32_e32 v173, v0
	v_lshlrev_b32_e32 v0, 16, v185
	v_max_f32_e32 v174, 0x1e3ce508, v0
	v_lshlrev_b32_e32 v0, 16, v181
	v_max_f32_e32 v0, 0x1e3ce508, v0
	v_rcp_f32_e32 v176, v0
	v_and_b32_e32 v0, 0xffff0000, v185
	v_max_f32_e32 v175, 0x1e3ce508, v0
	v_and_b32_e32 v0, 0xffff0000, v181
	v_max_f32_e32 v0, 0x1e3ce508, v0
	v_rcp_f32_e32 v177, v0
	v_lshlrev_b32_e32 v0, 16, v186
	v_pk_mul_f32 v[2:3], v[2:3], v[172:173]
	v_pk_mul_f32 v[56:57], v[56:57], v[2:3]
	v_max_f32_e32 v2, 0x1e3ce508, v0
	v_lshlrev_b32_e32 v0, 16, v182
	v_pk_mul_f32 v[172:173], v[174:175], v[176:177]
	v_max_f32_e32 v0, 0x1e3ce508, v0
	v_pk_mul_f32 v[58:59], v[58:59], v[172:173]
	v_rcp_f32_e32 v172, v0
	v_and_b32_e32 v0, 0xffff0000, v186
	v_max_f32_e32 v3, 0x1e3ce508, v0
	v_and_b32_e32 v0, 0xffff0000, v182
	v_max_f32_e32 v0, 0x1e3ce508, v0
	v_rcp_f32_e32 v173, v0
	v_lshlrev_b32_e32 v0, 16, v187
	v_max_f32_e32 v174, 0x1e3ce508, v0
	v_lshlrev_b32_e32 v0, 16, v183
	v_max_f32_e32 v0, 0x1e3ce508, v0
	v_rcp_f32_e32 v176, v0
	v_and_b32_e32 v0, 0xffff0000, v187
	v_max_f32_e32 v175, 0x1e3ce508, v0
	v_and_b32_e32 v0, 0xffff0000, v183
	v_max_f32_e32 v0, 0x1e3ce508, v0
	v_rcp_f32_e32 v177, v0
	v_lshlrev_b32_e32 v0, 16, v168
	v_pk_mul_f32 v[2:3], v[2:3], v[172:173]
	v_pk_mul_f32 v[52:53], v[52:53], v[2:3]
	v_max_f32_e32 v2, 0x1e3ce508, v0
	v_lshlrev_b32_e32 v0, 16, v164
	v_pk_mul_f32 v[172:173], v[174:175], v[176:177]
	v_max_f32_e32 v0, 0x1e3ce508, v0
	v_pk_mul_f32 v[54:55], v[54:55], v[172:173]
	v_rcp_f32_e32 v172, v0
	v_and_b32_e32 v0, 0xffff0000, v168
	v_max_f32_e32 v3, 0x1e3ce508, v0
	v_and_b32_e32 v0, 0xffff0000, v164
	v_max_f32_e32 v0, 0x1e3ce508, v0
	v_rcp_f32_e32 v173, v0
	v_lshlrev_b32_e32 v0, 16, v169
	v_max_f32_e32 v168, 0x1e3ce508, v0
	v_lshlrev_b32_e32 v0, 16, v165
	v_max_f32_e32 v0, 0x1e3ce508, v0
	v_rcp_f32_e32 v164, v0
	v_and_b32_e32 v0, 0xffff0000, v169
	v_max_f32_e32 v169, 0x1e3ce508, v0
	v_and_b32_e32 v0, 0xffff0000, v165
	v_max_f32_e32 v0, 0x1e3ce508, v0
	v_rcp_f32_e32 v165, v0
	v_lshlrev_b32_e32 v0, 16, v170
	v_pk_mul_f32 v[2:3], v[2:3], v[172:173]
	v_pk_mul_f32 v[24:25], v[24:25], v[2:3]
	v_max_f32_e32 v2, 0x1e3ce508, v0
	v_lshlrev_b32_e32 v0, 16, v166
	v_pk_mul_f32 v[164:165], v[168:169], v[164:165]
	v_max_f32_e32 v0, 0x1e3ce508, v0
	v_pk_mul_f32 v[26:27], v[26:27], v[164:165]
	v_rcp_f32_e32 v164, v0
	v_and_b32_e32 v0, 0xffff0000, v170
	v_max_f32_e32 v3, 0x1e3ce508, v0
	v_and_b32_e32 v0, 0xffff0000, v166
	v_max_f32_e32 v0, 0x1e3ce508, v0
	v_rcp_f32_e32 v165, v0
	v_lshlrev_b32_e32 v0, 16, v171
	v_max_f32_e32 v168, 0x1e3ce508, v0
	v_lshlrev_b32_e32 v0, 16, v167
	v_max_f32_e32 v0, 0x1e3ce508, v0
	v_rcp_f32_e32 v166, v0
	v_and_b32_e32 v0, 0xffff0000, v171
	v_max_f32_e32 v169, 0x1e3ce508, v0
	v_and_b32_e32 v0, 0xffff0000, v167
	v_max_f32_e32 v0, 0x1e3ce508, v0
	v_rcp_f32_e32 v167, v0
	v_lshlrev_b32_e32 v0, 16, v160
	v_pk_mul_f32 v[2:3], v[2:3], v[164:165]
	v_pk_mul_f32 v[20:21], v[20:21], v[2:3]
	v_max_f32_e32 v2, 0x1e3ce508, v0
	v_lshlrev_b32_e32 v0, 16, v156
	v_pk_mul_f32 v[164:165], v[168:169], v[166:167]
	v_max_f32_e32 v0, 0x1e3ce508, v0
	v_pk_mul_f32 v[22:23], v[22:23], v[164:165]
	v_rcp_f32_e32 v164, v0
	v_and_b32_e32 v0, 0xffff0000, v160
	v_max_f32_e32 v3, 0x1e3ce508, v0
	v_and_b32_e32 v0, 0xffff0000, v156
	v_max_f32_e32 v0, 0x1e3ce508, v0
	v_rcp_f32_e32 v165, v0
	v_lshlrev_b32_e32 v0, 16, v161
	v_max_f32_e32 v160, 0x1e3ce508, v0
	v_lshlrev_b32_e32 v0, 16, v157
	v_max_f32_e32 v0, 0x1e3ce508, v0
	v_rcp_f32_e32 v156, v0
	v_and_b32_e32 v0, 0xffff0000, v161
	v_max_f32_e32 v161, 0x1e3ce508, v0
	v_and_b32_e32 v0, 0xffff0000, v157
	v_max_f32_e32 v0, 0x1e3ce508, v0
	v_rcp_f32_e32 v157, v0
	v_lshlrev_b32_e32 v0, 16, v162
	v_pk_mul_f32 v[2:3], v[2:3], v[164:165]
	v_pk_mul_f32 v[48:49], v[48:49], v[2:3]
	v_max_f32_e32 v2, 0x1e3ce508, v0
	v_lshlrev_b32_e32 v0, 16, v158
	v_pk_mul_f32 v[156:157], v[160:161], v[156:157]
	v_max_f32_e32 v0, 0x1e3ce508, v0
	v_pk_mul_f32 v[50:51], v[50:51], v[156:157]
	v_rcp_f32_e32 v156, v0
	v_and_b32_e32 v0, 0xffff0000, v162
	v_max_f32_e32 v3, 0x1e3ce508, v0
	v_and_b32_e32 v0, 0xffff0000, v158
	v_max_f32_e32 v0, 0x1e3ce508, v0
	v_rcp_f32_e32 v157, v0
	v_lshlrev_b32_e32 v0, 16, v163
	v_max_f32_e32 v160, 0x1e3ce508, v0
	v_lshlrev_b32_e32 v0, 16, v159
	v_max_f32_e32 v0, 0x1e3ce508, v0
	v_rcp_f32_e32 v158, v0
	v_and_b32_e32 v0, 0xffff0000, v163
	v_max_f32_e32 v161, 0x1e3ce508, v0
	v_and_b32_e32 v0, 0xffff0000, v159
	v_max_f32_e32 v0, 0x1e3ce508, v0
	v_rcp_f32_e32 v159, v0
	v_lshlrev_b32_e32 v0, 16, v152
	v_pk_mul_f32 v[2:3], v[2:3], v[156:157]
	v_pk_mul_f32 v[44:45], v[44:45], v[2:3]
	v_max_f32_e32 v2, 0x1e3ce508, v0
	v_lshlrev_b32_e32 v0, 16, v148
	v_pk_mul_f32 v[156:157], v[160:161], v[158:159]
	v_max_f32_e32 v0, 0x1e3ce508, v0
	v_pk_mul_f32 v[46:47], v[46:47], v[156:157]
	v_rcp_f32_e32 v156, v0
	v_and_b32_e32 v0, 0xffff0000, v152
	v_max_f32_e32 v3, 0x1e3ce508, v0
	v_and_b32_e32 v0, 0xffff0000, v148
	v_max_f32_e32 v0, 0x1e3ce508, v0
	v_rcp_f32_e32 v157, v0
	v_lshlrev_b32_e32 v0, 16, v153
	v_max_f32_e32 v152, 0x1e3ce508, v0
	v_lshlrev_b32_e32 v0, 16, v149
	v_max_f32_e32 v0, 0x1e3ce508, v0
	v_rcp_f32_e32 v148, v0
	v_and_b32_e32 v0, 0xffff0000, v153
	v_max_f32_e32 v153, 0x1e3ce508, v0
	v_and_b32_e32 v0, 0xffff0000, v149
	v_max_f32_e32 v0, 0x1e3ce508, v0
	v_rcp_f32_e32 v149, v0
	v_lshlrev_b32_e32 v0, 16, v154
	v_pk_mul_f32 v[2:3], v[2:3], v[156:157]
	v_pk_mul_f32 v[16:17], v[16:17], v[2:3]
	v_max_f32_e32 v2, 0x1e3ce508, v0
	v_lshlrev_b32_e32 v0, 16, v150
	v_pk_mul_f32 v[148:149], v[152:153], v[148:149]
	v_max_f32_e32 v0, 0x1e3ce508, v0
	v_pk_mul_f32 v[18:19], v[18:19], v[148:149]
	v_rcp_f32_e32 v148, v0
	v_and_b32_e32 v0, 0xffff0000, v154
	v_max_f32_e32 v3, 0x1e3ce508, v0
	v_and_b32_e32 v0, 0xffff0000, v150
	v_max_f32_e32 v0, 0x1e3ce508, v0
	v_rcp_f32_e32 v149, v0
	v_lshlrev_b32_e32 v0, 16, v155
	v_max_f32_e32 v152, 0x1e3ce508, v0
	v_lshlrev_b32_e32 v0, 16, v151
	v_max_f32_e32 v0, 0x1e3ce508, v0
	v_rcp_f32_e32 v150, v0
	v_and_b32_e32 v0, 0xffff0000, v155
	v_max_f32_e32 v153, 0x1e3ce508, v0
	v_and_b32_e32 v0, 0xffff0000, v151
	v_max_f32_e32 v0, 0x1e3ce508, v0
	v_rcp_f32_e32 v151, v0
	v_lshlrev_b32_e32 v0, 16, v144
	v_pk_mul_f32 v[2:3], v[2:3], v[148:149]
	v_pk_mul_f32 v[12:13], v[12:13], v[2:3]
	v_max_f32_e32 v2, 0x1e3ce508, v0
	v_lshlrev_b32_e32 v0, 16, v140
	v_pk_mul_f32 v[148:149], v[152:153], v[150:151]
	v_max_f32_e32 v0, 0x1e3ce508, v0
	v_pk_mul_f32 v[14:15], v[14:15], v[148:149]
	v_rcp_f32_e32 v148, v0
	v_and_b32_e32 v0, 0xffff0000, v144
	v_max_f32_e32 v3, 0x1e3ce508, v0
	v_and_b32_e32 v0, 0xffff0000, v140
	v_max_f32_e32 v0, 0x1e3ce508, v0
	v_rcp_f32_e32 v149, v0
	v_lshlrev_b32_e32 v0, 16, v145
	v_max_f32_e32 v144, 0x1e3ce508, v0
	v_lshlrev_b32_e32 v0, 16, v141
	v_max_f32_e32 v0, 0x1e3ce508, v0
	v_rcp_f32_e32 v140, v0
	v_and_b32_e32 v0, 0xffff0000, v145
	v_max_f32_e32 v145, 0x1e3ce508, v0
	v_and_b32_e32 v0, 0xffff0000, v141
	v_max_f32_e32 v0, 0x1e3ce508, v0
	v_rcp_f32_e32 v141, v0
	v_lshlrev_b32_e32 v0, 16, v146
	v_pk_mul_f32 v[2:3], v[2:3], v[148:149]
	v_pk_mul_f32 v[40:41], v[40:41], v[2:3]
	v_max_f32_e32 v2, 0x1e3ce508, v0
	v_lshlrev_b32_e32 v0, 16, v142
	v_pk_mul_f32 v[140:141], v[144:145], v[140:141]
	v_max_f32_e32 v0, 0x1e3ce508, v0
	v_pk_mul_f32 v[42:43], v[42:43], v[140:141]
	v_rcp_f32_e32 v140, v0
	v_and_b32_e32 v0, 0xffff0000, v146
	v_max_f32_e32 v3, 0x1e3ce508, v0
	v_and_b32_e32 v0, 0xffff0000, v142
	v_max_f32_e32 v0, 0x1e3ce508, v0
	v_rcp_f32_e32 v141, v0
	v_lshlrev_b32_e32 v0, 16, v147
	v_max_f32_e32 v144, 0x1e3ce508, v0
	v_lshlrev_b32_e32 v0, 16, v143
	v_max_f32_e32 v0, 0x1e3ce508, v0
	v_rcp_f32_e32 v142, v0
	v_and_b32_e32 v0, 0xffff0000, v147
	v_max_f32_e32 v145, 0x1e3ce508, v0
	v_and_b32_e32 v0, 0xffff0000, v143
	v_max_f32_e32 v0, 0x1e3ce508, v0
	v_rcp_f32_e32 v143, v0
	v_lshlrev_b32_e32 v0, 16, v136
	v_pk_mul_f32 v[2:3], v[2:3], v[140:141]
	v_pk_mul_f32 v[36:37], v[36:37], v[2:3]
	v_max_f32_e32 v2, 0x1e3ce508, v0
	v_lshlrev_b32_e32 v0, 16, v132
	v_pk_mul_f32 v[140:141], v[144:145], v[142:143]
	v_max_f32_e32 v0, 0x1e3ce508, v0
	v_pk_mul_f32 v[38:39], v[38:39], v[140:141]
	v_rcp_f32_e32 v140, v0
	v_and_b32_e32 v0, 0xffff0000, v136
	v_max_f32_e32 v3, 0x1e3ce508, v0
	v_and_b32_e32 v0, 0xffff0000, v132
	v_max_f32_e32 v0, 0x1e3ce508, v0
	v_rcp_f32_e32 v141, v0
	v_lshlrev_b32_e32 v0, 16, v137
	v_max_f32_e32 v136, 0x1e3ce508, v0
	v_lshlrev_b32_e32 v0, 16, v133
	v_max_f32_e32 v0, 0x1e3ce508, v0
	v_rcp_f32_e32 v132, v0
	v_and_b32_e32 v0, 0xffff0000, v137
	v_max_f32_e32 v137, 0x1e3ce508, v0
	v_and_b32_e32 v0, 0xffff0000, v133
	v_max_f32_e32 v0, 0x1e3ce508, v0
	v_rcp_f32_e32 v133, v0
	v_lshlrev_b32_e32 v0, 16, v138
	v_pk_mul_f32 v[2:3], v[2:3], v[140:141]
	v_pk_mul_f32 v[8:9], v[8:9], v[2:3]
	v_max_f32_e32 v2, 0x1e3ce508, v0
	v_lshlrev_b32_e32 v0, 16, v134
	v_pk_mul_f32 v[132:133], v[136:137], v[132:133]
	v_max_f32_e32 v0, 0x1e3ce508, v0
	v_pk_mul_f32 v[10:11], v[10:11], v[132:133]
	v_rcp_f32_e32 v132, v0
	v_and_b32_e32 v0, 0xffff0000, v138
	v_max_f32_e32 v3, 0x1e3ce508, v0
	v_and_b32_e32 v0, 0xffff0000, v134
	v_max_f32_e32 v0, 0x1e3ce508, v0
	v_rcp_f32_e32 v133, v0
	v_lshlrev_b32_e32 v0, 16, v139
	v_max_f32_e32 v136, 0x1e3ce508, v0
	v_lshlrev_b32_e32 v0, 16, v135
	v_max_f32_e32 v0, 0x1e3ce508, v0
	v_rcp_f32_e32 v134, v0
	v_and_b32_e32 v0, 0xffff0000, v139
	v_max_f32_e32 v137, 0x1e3ce508, v0
	v_and_b32_e32 v0, 0xffff0000, v135
	v_max_f32_e32 v0, 0x1e3ce508, v0
	v_rcp_f32_e32 v135, v0
	v_pk_mul_f32 v[2:3], v[2:3], v[132:133]
	v_pk_mul_f32 v[132:133], v[136:137], v[134:135]
	s_nop 0
	v_pk_mul_f32 v[6:7], v[6:7], v[132:133]
	v_pk_mul_f32 v[4:5], v[4:5], v[2:3]
	s_and_b64 vcc, exec, s[34:35]
	s_mov_b64 s[0:1], -1
	s_cbranch_vccnz .LBB0_1222
